# MLA attention K/V LDS double buffer (second set at +0x10000, XOR-toggled address regs), loop-top barrier removed
# speedup vs baseline: 1.0703x; 1.0010x over previous
.LBB0_555:
	s_or_b64 exec, exec, s[22:23]
	v_xor_b32_e32 v188, 0x10000, v188
	v_xor_b32_e32 v189, 0x10000, v189
	v_xor_b32_e32 v190, 0x10000, v190
	v_xor_b32_e32 v191, 0x10000, v191
	v_xor_b32_e32 v192, 0x10000, v192
	v_xor_b32_e32 v193, 0x10000, v193
	v_xor_b32_e32 v194, 0x10000, v194
	v_readlane_b32 s12, v253, 29
	v_readlane_b32 s13, v253, 30
	s_add_i32 s12, s12, 64
	s_add_i32 s58, s58, 1
	v_writelane_b32 v253, s12, 29
	s_cmp_eq_u32 s57, s58
	s_nop 0
	v_writelane_b32 v253, s13, 30
	s_cbranch_scc1 .LBB0_573
.LBB0_556:
	s_and_saveexec_b64 s[12:13], s[6:7]
	s_cbranch_execnz .LBB0_568
	s_or_b64 exec, exec, s[12:13]
	s_and_saveexec_b64 s[12:13], s[8:9]
	s_cbranch_execnz .LBB0_569

.LBB0_587:
	s_or_b64 exec, exec, s[24:25]
	v_xor_b32_e32 v185, 0x10000, v185
	v_xor_b32_e32 v186, 0x10000, v186
	v_xor_b32_e32 v187, 0x10000, v187
	v_xor_b32_e32 v188, 0x10000, v188
	v_xor_b32_e32 v189, 0x10000, v189
	v_xor_b32_e32 v190, 0x10000, v190
	v_xor_b32_e32 v191, 0x10000, v191
	s_mov_b64 s[24:25], 0x5000
	s_add_i32 s26, s26, 1
	v_lshl_add_u64 v[172:173], v[172:173], 0, s[24:25]
	v_lshl_add_u64 v[174:175], v[174:175], 0, s[24:25]
	v_lshl_add_u64 v[176:177], v[176:177], 0, s[24:25]
	s_mov_b64 s[24:25], 0x80
	v_lshl_add_u64 v[178:179], v[178:179], 0, s[24:25]
	s_cmp_eq_u32 s26, 33
	v_lshl_add_u64 v[180:181], v[180:181], 0, s[24:25]
	s_cbranch_scc1 .LBB0_604
.LBB0_588:
	s_and_saveexec_b64 s[24:25], s[8:9]
	s_cbranch_execnz .LBB0_600
	s_or_b64 exec, exec, s[24:25]
	s_and_saveexec_b64 s[24:25], s[10:11]
	s_cbranch_execnz .LBB0_601
